# adds pipelined work-queue dequeue (next item index prefetched by wave 0 during the current item) and fast-path fall-through layout of the diff-attention loop (rare re-reference blocks moved out of lin
# speedup vs baseline: 1.0111x; 1.0111x over previous
.LBB0_86:
	s_andn2_b64 vcc, exec, s[2:3]
	v_writelane_b32 v254, s12, 54
	s_cbranch_vccnz .LBB0_570
	s_add_i32 s0, s12, -1
	s_mul_hi_i32 s1, s0, 0x92492493
	s_add_i32 s1, s1, s0
	s_lshr_b32 s2, s1, 31
	s_ashr_i32 s1, s1, 2
	s_add_i32 s2, s1, s2
	s_mul_i32 s1, s2, 7
	s_sub_i32 s47, s0, s1
	s_sub_i32 s0, s12, 22
	s_cmp_lt_u32 s0, 7
	s_cselect_b64 s[38:39], -1, 0
	s_cmp_gt_u32 s0, 6
	s_cselect_b64 s[0:1], -1, 0
	v_writelane_b32 v254, s0, 55
	s_mov_b64 s[50:51], 0
	s_nop 0
	v_writelane_b32 v254, s1, 56
	s_add_i32 s0, s12, 5
	v_readlane_b32 s56, v254, 4
	s_cmp_lt_u32 s0, 13
	v_readlane_b32 s70, v254, 18
	v_readlane_b32 s71, v254, 19
	s_cselect_b32 s48, s73, s71
	s_cselect_b32 s49, s72, s70
	s_ashr_i32 s3, s2, 31
	v_readlane_b32 s57, v254, 5
	v_readlane_b32 s58, v254, 6
	v_readlane_b32 s59, v254, 7
	v_readlane_b32 s60, v254, 8
	v_readlane_b32 s61, v254, 9
	v_readlane_b32 s62, v254, 10
	v_readlane_b32 s63, v254, 11
	v_readlane_b32 s64, v254, 12
	v_readlane_b32 s65, v254, 13
	v_readlane_b32 s66, v254, 14
	v_readlane_b32 s67, v254, 15
	v_readlane_b32 s68, v254, 16
	v_readlane_b32 s69, v254, 17
	s_mul_hi_i32 s0, s2, 0x36000
	v_writelane_b32 v254, s2, 57
	s_mul_i32 s1, s2, 0x36000
	s_mov_b64 s[58:59], 0
	v_writelane_b32 v254, s3, 58
	v_readlane_b32 s2, v251, 3
	v_readlane_b32 s3, v251, 4
	s_add_u32 s44, s2, s1
	s_addc_u32 s45, s3, s0
	v_writelane_b32 v254, s44, 59
	s_mov_b64 s[0:1], -1
	s_cmp_lt_i32 s47, 1
	v_writelane_b32 v254, s45, 60
	v_writelane_b32 v254, s47, 61
	s_cbranch_scc1 .LBB0_414
	s_cmp_gt_i32 s47, 1
	s_cbranch_scc0 .LBB0_263
	s_cmp_eq_u32 s47, 2
	s_mov_b64 s[58:59], -1
	s_cbranch_scc0 .LBB0_262
	s_and_b64 s[0:1], s[38:39], exec
	s_movk_i32 s0, 0x600
	s_cselect_b32 s37, s0, 0x610
	s_movk_i32 s0, 0x618
	s_cselect_b32 s41, 0x600, s0
	s_movk_i32 s0, 0x638
	s_cselect_b32 s92, 0x600, s0
	s_movk_i32 s0, 0x658
	s_cselect_b32 s93, 0x600, s0
	s_movk_i32 s0, 0x918
	v_readlane_b32 s18, v254, 57
	s_cselect_b32 s94, 0x600, s0
	s_lshl_b32 s0, s18, 6
	s_ashr_i32 s1, s0, 31
	s_lshl_b64 s[0:1], s[0:1], 2
	s_add_u32 s22, s88, s0
	s_addc_u32 s23, s89, s1
	s_lshl_b32 s16, s18, 9
	v_readlane_b32 s19, v254, 58
	s_add_i32 s2, s18, 1
	v_writelane_b32 v254, s16, 62
	s_ashr_i32 s3, s2, 31
	s_waitcnt lgkmcnt(0)
	s_lshl_b32 s8, s18, 1
	s_lshl_b32 s10, s18, 8
	v_readlane_b32 s72, v254, 4
	s_lshl_b64 s[4:5], s[2:3], 24
	s_lshl_b64 s[6:7], s[2:3], 23
	s_lshl_b32 s95, s18, 2
	s_ashr_i32 s9, s8, 31
	s_ashr_i32 s11, s10, 31
	v_readlane_b32 s82, v254, 14
	v_readlane_b32 s83, v254, 15
	s_add_u32 s16, s82, s4
	s_addc_u32 s17, s83, s5
	v_readlane_b32 s73, v254, 5
	v_readlane_b32 s74, v254, 6
	v_readlane_b32 s75, v254, 7
	v_readlane_b32 s76, v254, 8
	v_readlane_b32 s77, v254, 9
	v_readlane_b32 s78, v254, 10
	v_readlane_b32 s79, v254, 11
	v_readlane_b32 s80, v254, 12
	v_readlane_b32 s81, v254, 13
	v_readlane_b32 s84, v254, 16
	v_readlane_b32 s85, v254, 17
	v_readlane_b32 s86, v254, 18
	v_readlane_b32 s87, v254, 19
	v_writelane_b32 v254, s16, 63
	v_readlane_b32 s56, v252, 35
	v_readlane_b32 s58, v252, 37
	v_writelane_b32 v255, s17, 0
	v_readlane_b32 s16, v252, 55
	s_add_u32 s24, s16, s6
	v_readlane_b32 s16, v252, 56
	s_addc_u32 s25, s16, s7
	v_writelane_b32 v255, s24, 1
	s_add_u32 s4, s80, s4
	s_addc_u32 s5, s81, s5
	v_writelane_b32 v255, s25, 2
	v_writelane_b32 v255, s4, 3
	v_readlane_b32 s59, v252, 38
	s_mul_hi_i32 s12, s2, 0x900000
	v_writelane_b32 v255, s5, 4
	v_readlane_b32 s4, v252, 57
	s_add_u32 s6, s4, s6
	v_readlane_b32 s4, v252, 58
	s_addc_u32 s7, s4, s7
	s_lshl_b64 s[4:5], s[2:3], 22
	v_writelane_b32 v255, s6, 5
	s_add_u32 s4, s58, s4
	s_addc_u32 s5, s59, s5
	v_writelane_b32 v255, s7, 6
	v_writelane_b32 v255, s4, 7
	s_mul_i32 s13, s2, 0x900000
	s_mul_hi_i32 s14, s2, 0x500000
	s_mul_i32 s15, s2, 0x500000
	v_writelane_b32 v255, s5, 8
	s_lshl_b64 s[2:3], s[2:3], 21
	v_readlane_b32 s4, v252, 59
	s_add_u32 s4, s4, s2
	v_readlane_b32 s2, v252, 60
	s_addc_u32 s5, s2, s3
	v_readlane_b32 s57, v252, 36
	s_add_u32 s2, s56, s13
	s_addc_u32 s3, s57, s12
	v_writelane_b32 v255, s4, 9
	s_add_u32 s2, s2, 0x400
	s_addc_u32 s3, s3, 0
	v_writelane_b32 v255, s5, 10
	v_writelane_b32 v255, s2, 11
	v_readlane_b32 s4, v252, 20
	v_readlane_b32 s5, v252, 21
	v_writelane_b32 v255, s3, 12
	s_add_u32 s2, s88, s15
	s_addc_u32 s3, s89, s14
	s_add_u32 s2, s2, 0x500000
	s_addc_u32 s3, s3, 0
	v_writelane_b32 v255, s2, 13
	v_readlane_b32 s70, v252, 49
	v_readlane_b32 s71, v252, 50
	v_writelane_b32 v255, s3, 14
	s_lshl_b64 s[2:3], s[8:9], 2
	s_add_u32 s2, s4, s2
	s_addc_u32 s3, s5, s3
	s_add_u32 s0, s78, s0
	s_addc_u32 s1, s79, s1
	v_readlane_b32 s62, v252, 41
	v_readlane_b32 s66, v252, 45
	v_readlane_b32 s67, v252, 46
	s_mov_b64 s[70:71], s[0:1]
	s_lshl_b64 s[0:1], s[10:11], 2
	v_readlane_b32 s63, v252, 42
	s_mov_b64 s[66:67], s[2:3]
	s_add_u32 s2, s62, s0
	v_readlane_b32 s64, v252, 43
	s_addc_u32 s3, s63, s1
	v_readlane_b32 s65, v252, 44
	v_writelane_b32 v255, s2, 15
	s_add_u32 s0, s64, s0
	s_addc_u32 s1, s65, s1
	v_writelane_b32 v255, s3, 16
	v_writelane_b32 v255, s0, 17
	v_readlane_b32 s60, v252, 39
	v_readlane_b32 s61, v252, 40
	v_writelane_b32 v255, s1, 18
	s_mul_i32 s0, s18, 0x744
	v_readlane_b32 s68, v252, 47
	v_readlane_b32 s69, v252, 48
	s_mov_b32 s13, 0x800000
	s_mov_b64 s[64:65], s[22:23]
	v_writelane_b32 v255, s0, 19
	s_mov_b64 s[10:11], 0x8000
	v_readfirstlane_b32 s98, v155
	s_lshr_b32 s98, s98, 6
	s_cmp_lg_u32 s98, 0
	s_cbranch_scc1 .Ldq_noprime
	s_mov_b64 s[0:1], exec
	s_mov_b32 s2, 0
	s_mov_b32 s3, 1
	s_mov_b64 exec, s[2:3]
	global_atomic_add v255, v1, v157, s[64:65] sc0
	s_mov_b64 exec, s[0:1]
.Ldq_noprime:
	s_branch .LBB0_94
.LBB0_91:
	s_waitcnt vmcnt(0)
	s_mov_b64 s[10:11], 0x8000
	s_barrier

.LBB0_94:
	s_barrier
	s_mov_b64 s[0:1], exec
	v_readfirstlane_b32 s98, v155
	s_lshr_b32 s98, s98, 6
	s_cmp_lg_u32 s98, 0
	s_cbranch_scc1 .LBB0_98
	s_waitcnt vmcnt(0)
	v_readlane_b32 s98, v255, 32
	v_readlane_b32 s99, v253, 61
	s_mov_b32 s2, 0
	s_mov_b32 s3, 1
	s_mov_b64 exec, s[2:3]
	v_mov_b32_e32 v0, s98
	v_mov_b32_e32 v2, s99
	ds_write_b32 v2, v0
	global_atomic_add v255, v1, v157, s[64:65] sc0

.Ldl_slow1:
	v_max_f32_e32 v182, v99, v99
	v_max_f32_e32 v183, v115, v115
	v_max_f32_e32 v182, v183, v182
	v_max_f32_e32 v183, v100, v100
	v_max_f32_e32 v184, v116, v116
	v_max_f32_e32 v183, v184, v183
	v_max_f32_e32 v184, v101, v101
	v_max_f32_e32 v185, v117, v117
	v_max3_f32 v182, v114, v98, v182
	v_max_f32_e32 v184, v185, v184
	v_max3_f32 v182, v182, v183, v184
	v_max_f32_e32 v183, v102, v102
	v_max_f32_e32 v184, v118, v118
	v_max_f32_e32 v183, v184, v183
	v_max_f32_e32 v184, v103, v103
	v_max_f32_e32 v185, v119, v119
	v_max_f32_e32 v184, v185, v184
	v_max3_f32 v182, v182, v183, v184
	v_max_f32_e32 v183, v104, v104
	v_max_f32_e32 v184, v120, v120
	v_max_f32_e32 v183, v184, v183
	v_max_f32_e32 v184, v105, v105
	v_max_f32_e32 v185, v121, v121
	v_max_f32_e32 v184, v185, v184
	v_max3_f32 v182, v182, v183, v184
	v_max_f32_e32 v183, v106, v106
	v_max_f32_e32 v184, v122, v122
	v_max_f32_e32 v183, v184, v183
	v_max_f32_e32 v184, v107, v107
	v_max_f32_e32 v185, v123, v123
	v_max_f32_e32 v184, v185, v184
	v_max3_f32 v182, v182, v183, v184
	v_max_f32_e32 v183, v108, v108
	v_max_f32_e32 v184, v124, v124
	v_max_f32_e32 v183, v184, v183
	v_max_f32_e32 v184, v109, v109
	v_max_f32_e32 v185, v125, v125
	v_max_f32_e32 v184, v185, v184
	v_max3_f32 v182, v182, v183, v184
	v_max_f32_e32 v183, v110, v110
	v_max_f32_e32 v184, v126, v126
	v_max_f32_e32 v183, v184, v183
	v_max_f32_e32 v184, v111, v111
	v_max_f32_e32 v185, v127, v127
	v_max_f32_e32 v184, v185, v184
	v_max3_f32 v182, v182, v183, v184
	v_max_f32_e32 v183, v112, v112
	v_max_f32_e32 v184, v128, v128
	v_max_f32_e32 v183, v184, v183
	v_max_f32_e32 v184, v113, v113
	v_max_f32_e32 v185, v129, v129
	v_max_f32_e32 v184, v185, v184
	v_max3_f32 v182, v182, v183, v184
	ds_bpermute_b32 v183, v236, v182
	s_waitcnt lgkmcnt(0)
	v_max3_f32 v182, v182, v183, 0
	v_exp_f32_e64 v184, -v182
	v_sub_f32_e32 v114, v114, v182
	v_sub_f32_e32 v115, v115, v182
	v_sub_f32_e32 v98, v98, v182
	v_sub_f32_e32 v99, v99, v182
	v_exp_f32_e32 v188, v114
	v_exp_f32_e32 v189, v115
	v_mul_f32_e32 v176, v176, v184
	v_pk_mul_f32 v[16:17], v[16:17], v[184:185] op_sel_hi:[1,0]
	v_pk_mul_f32 v[14:15], v[14:15], v[184:185] op_sel_hi:[1,0]
	v_pk_mul_f32 v[12:13], v[12:13], v[184:185] op_sel_hi:[1,0]
	v_pk_mul_f32 v[10:11], v[10:11], v[184:185] op_sel_hi:[1,0]
	v_pk_mul_f32 v[8:9], v[8:9], v[184:185] op_sel_hi:[1,0]
	v_pk_mul_f32 v[6:7], v[6:7], v[184:185] op_sel_hi:[1,0]
	v_pk_mul_f32 v[4:5], v[4:5], v[184:185] op_sel_hi:[1,0]
	v_pk_mul_f32 v[2:3], v[2:3], v[184:185] op_sel_hi:[1,0]
	v_pk_mul_f32 v[32:33], v[32:33], v[184:185] op_sel_hi:[1,0]
	v_pk_mul_f32 v[30:31], v[30:31], v[184:185] op_sel_hi:[1,0]
	v_pk_mul_f32 v[28:29], v[28:29], v[184:185] op_sel_hi:[1,0]
	v_pk_mul_f32 v[26:27], v[26:27], v[184:185] op_sel_hi:[1,0]
	v_pk_mul_f32 v[24:25], v[24:25], v[184:185] op_sel_hi:[1,0]
	v_pk_mul_f32 v[22:23], v[22:23], v[184:185] op_sel_hi:[1,0]
	v_pk_mul_f32 v[20:21], v[20:21], v[184:185] op_sel_hi:[1,0]
	v_pk_mul_f32 v[18:19], v[18:19], v[184:185] op_sel_hi:[1,0]
	v_sub_f32_e32 v116, v116, v182
	v_sub_f32_e32 v117, v117, v182
	v_exp_f32_e32 v184, v98
	v_exp_f32_e32 v185, v99
	v_sub_f32_e32 v100, v100, v182
	v_sub_f32_e32 v101, v101, v182
	v_exp_f32_e32 v192, v116
	v_exp_f32_e32 v193, v117
	v_sub_f32_e32 v118, v118, v182
	v_sub_f32_e32 v119, v119, v182
	v_exp_f32_e32 v186, v100
	v_exp_f32_e32 v187, v101
	v_sub_f32_e32 v102, v102, v182
	v_sub_f32_e32 v103, v103, v182
	v_pk_add_f32 v[98:99], v[188:189], 0 op_sel_hi:[1,0]
	v_exp_f32_e32 v196, v118
	v_exp_f32_e32 v197, v119
	v_sub_f32_e32 v120, v120, v182
	v_sub_f32_e32 v121, v121, v182
	v_pk_add_f32 v[98:99], v[184:185], v[98:99]
	v_exp_f32_e32 v190, v102
	v_exp_f32_e32 v191, v103
	v_sub_f32_e32 v104, v104, v182
	v_sub_f32_e32 v105, v105, v182
	v_pk_add_f32 v[98:99], v[98:99], v[192:193]
	v_exp_f32_e32 v202, v120
	v_exp_f32_e32 v203, v121
	v_sub_f32_e32 v122, v122, v182
	v_sub_f32_e32 v123, v123, v182
	v_pk_add_f32 v[98:99], v[186:187], v[98:99]
	v_exp_f32_e32 v194, v104
	v_exp_f32_e32 v195, v105
	v_sub_f32_e32 v106, v106, v182
	v_sub_f32_e32 v107, v107, v182
	v_pk_add_f32 v[98:99], v[98:99], v[196:197]
	v_exp_f32_e32 v204, v122
	v_exp_f32_e32 v205, v123
	v_sub_f32_e32 v124, v124, v182
	v_sub_f32_e32 v125, v125, v182
	v_pk_add_f32 v[98:99], v[190:191], v[98:99]
	v_exp_f32_e32 v198, v106
	v_exp_f32_e32 v199, v107
	v_sub_f32_e32 v108, v108, v182
	v_sub_f32_e32 v109, v109, v182
	v_pk_add_f32 v[98:99], v[98:99], v[202:203]
	v_exp_f32_e32 v208, v124
	v_exp_f32_e32 v209, v125
	v_sub_f32_e32 v126, v126, v182
	v_sub_f32_e32 v127, v127, v182
	v_pk_add_f32 v[98:99], v[194:195], v[98:99]
	v_exp_f32_e32 v200, v108
	v_exp_f32_e32 v201, v109
	v_sub_f32_e32 v110, v110, v182
	v_sub_f32_e32 v111, v111, v182
	v_pk_add_f32 v[98:99], v[98:99], v[204:205]
	v_exp_f32_e32 v212, v126
	v_exp_f32_e32 v213, v127
	v_sub_f32_e32 v128, v128, v182
	v_sub_f32_e32 v129, v129, v182
	v_pk_add_f32 v[98:99], v[198:199], v[98:99]
	v_exp_f32_e32 v206, v110
	v_exp_f32_e32 v207, v111
	v_sub_f32_e32 v112, v112, v182
	v_sub_f32_e32 v113, v113, v182
	v_pk_add_f32 v[98:99], v[98:99], v[208:209]
	v_exp_f32_e32 v214, v128
	v_exp_f32_e32 v215, v129
	v_pk_add_f32 v[98:99], v[200:201], v[98:99]
	v_exp_f32_e32 v210, v112
	v_exp_f32_e32 v211, v113
	v_pk_add_f32 v[98:99], v[98:99], v[212:213]
	v_mov_b32_e32 v100, v174
	v_pk_add_f32 v[98:99], v[206:207], v[98:99]
	s_nop 0
	v_pk_add_f32 v[98:99], v[98:99], v[214:215]
	s_nop 0
	v_pk_add_f32 v[98:99], v[210:211], v[98:99]
	s_nop 0
	v_mov_b32_e32 v101, v98
	v_mov_b32_e32 v183, v99
	v_pk_add_f32 v[182:183], v[100:101], v[182:183]
	s_nop 0
	v_mov_b32_e32 v237, v183
	s_branch .LBB0_236
.Ldl_slow2:
	v_max_f32_e32 v183, v67, v67
	v_max_f32_e32 v184, v83, v83
	v_max_f32_e32 v183, v184, v183
	v_max_f32_e32 v184, v68, v68
	v_max_f32_e32 v185, v84, v84
	v_max_f32_e32 v184, v185, v184
	v_max_f32_e32 v185, v69, v69
	v_max_f32_e32 v186, v85, v85
	v_max3_f32 v183, v82, v66, v183
	v_max_f32_e32 v185, v186, v185
	v_max3_f32 v183, v183, v184, v185
	v_max_f32_e32 v184, v70, v70
	v_max_f32_e32 v185, v86, v86
	v_max_f32_e32 v184, v185, v184
	v_max_f32_e32 v185, v71, v71
	v_max_f32_e32 v186, v87, v87
	v_max_f32_e32 v185, v186, v185
	v_max3_f32 v183, v183, v184, v185
	v_max_f32_e32 v184, v72, v72
	v_max_f32_e32 v185, v88, v88
	v_max_f32_e32 v184, v185, v184
	v_max_f32_e32 v185, v73, v73
	v_max_f32_e32 v186, v89, v89
	v_max_f32_e32 v185, v186, v185
	v_max3_f32 v183, v183, v184, v185
	v_max_f32_e32 v184, v74, v74
	v_max_f32_e32 v185, v90, v90
	v_max_f32_e32 v184, v185, v184
	v_max_f32_e32 v185, v75, v75
	v_max_f32_e32 v186, v91, v91
	v_max_f32_e32 v185, v186, v185
	v_max3_f32 v183, v183, v184, v185
	v_max_f32_e32 v184, v76, v76
	v_max_f32_e32 v185, v92, v92
	v_max_f32_e32 v184, v185, v184
	v_max_f32_e32 v185, v77, v77
	v_max_f32_e32 v186, v93, v93
	v_max_f32_e32 v185, v186, v185
	v_max3_f32 v183, v183, v184, v185
	v_max_f32_e32 v184, v78, v78
	v_max_f32_e32 v185, v94, v94
	v_max_f32_e32 v184, v185, v184
	v_max_f32_e32 v185, v79, v79
	v_max_f32_e32 v186, v95, v95
	v_max_f32_e32 v185, v186, v185
	v_max3_f32 v183, v183, v184, v185
	v_max_f32_e32 v184, v80, v80
	v_max_f32_e32 v185, v96, v96
	v_max_f32_e32 v184, v185, v184
	v_max_f32_e32 v185, v81, v81
	v_max_f32_e32 v186, v97, v97
	v_max_f32_e32 v185, v186, v185
	v_max3_f32 v183, v183, v184, v185
	ds_bpermute_b32 v184, v236, v183
	s_waitcnt lgkmcnt(0)
	v_max3_f32 v216, v183, v184, 0
	v_exp_f32_e64 v184, -v216
	v_sub_f32_e32 v82, v82, v216
	v_sub_f32_e32 v83, v83, v216
	v_sub_f32_e32 v66, v66, v216
	v_sub_f32_e32 v67, v67, v216
	v_exp_f32_e32 v190, v82
	v_exp_f32_e32 v191, v83
	v_mul_f32_e32 v177, v177, v184
	v_pk_mul_f32 v[48:49], v[48:49], v[184:185] op_sel_hi:[1,0]
	v_pk_mul_f32 v[46:47], v[46:47], v[184:185] op_sel_hi:[1,0]
	v_pk_mul_f32 v[44:45], v[44:45], v[184:185] op_sel_hi:[1,0]
	v_pk_mul_f32 v[42:43], v[42:43], v[184:185] op_sel_hi:[1,0]
	v_pk_mul_f32 v[40:41], v[40:41], v[184:185] op_sel_hi:[1,0]
	v_pk_mul_f32 v[38:39], v[38:39], v[184:185] op_sel_hi:[1,0]
	v_pk_mul_f32 v[36:37], v[36:37], v[184:185] op_sel_hi:[1,0]
	v_pk_mul_f32 v[34:35], v[34:35], v[184:185] op_sel_hi:[1,0]
	v_pk_mul_f32 v[64:65], v[64:65], v[184:185] op_sel_hi:[1,0]
	v_pk_mul_f32 v[62:63], v[62:63], v[184:185] op_sel_hi:[1,0]
	v_pk_mul_f32 v[60:61], v[60:61], v[184:185] op_sel_hi:[1,0]
	v_pk_mul_f32 v[58:59], v[58:59], v[184:185] op_sel_hi:[1,0]
	v_pk_mul_f32 v[56:57], v[56:57], v[184:185] op_sel_hi:[1,0]
	v_pk_mul_f32 v[54:55], v[54:55], v[184:185] op_sel_hi:[1,0]
	v_pk_mul_f32 v[52:53], v[52:53], v[184:185] op_sel_hi:[1,0]
	v_pk_mul_f32 v[50:51], v[50:51], v[184:185] op_sel_hi:[1,0]
	v_sub_f32_e32 v84, v84, v216
	v_sub_f32_e32 v85, v85, v216
	v_exp_f32_e32 v184, v66
	v_exp_f32_e32 v185, v67
	v_sub_f32_e32 v68, v68, v216
	v_sub_f32_e32 v69, v69, v216
	v_exp_f32_e32 v194, v84
	v_exp_f32_e32 v195, v85
	v_sub_f32_e32 v86, v86, v216
	v_sub_f32_e32 v87, v87, v216
	v_exp_f32_e32 v186, v68
	v_exp_f32_e32 v187, v69
	v_sub_f32_e32 v70, v70, v216
	v_sub_f32_e32 v71, v71, v216
	v_pk_add_f32 v[66:67], v[190:191], 0 op_sel_hi:[1,0]
	v_exp_f32_e32 v200, v86
	v_exp_f32_e32 v201, v87
	v_sub_f32_e32 v88, v88, v216
	v_sub_f32_e32 v89, v89, v216
	v_pk_add_f32 v[66:67], v[184:185], v[66:67]
	v_exp_f32_e32 v188, v70
	v_exp_f32_e32 v189, v71
	v_sub_f32_e32 v72, v72, v216
	v_sub_f32_e32 v73, v73, v216
	v_pk_add_f32 v[66:67], v[66:67], v[194:195]
	v_exp_f32_e32 v206, v88
	v_exp_f32_e32 v207, v89
	v_sub_f32_e32 v90, v90, v216
	v_sub_f32_e32 v91, v91, v216
	v_pk_add_f32 v[66:67], v[186:187], v[66:67]
	v_exp_f32_e32 v192, v72
	v_exp_f32_e32 v193, v73
	v_sub_f32_e32 v74, v74, v216
	v_sub_f32_e32 v75, v75, v216
	v_pk_add_f32 v[66:67], v[66:67], v[200:201]
	v_exp_f32_e32 v198, v90
	v_exp_f32_e32 v199, v91
	v_sub_f32_e32 v92, v92, v216
	v_sub_f32_e32 v93, v93, v216
	v_pk_add_f32 v[66:67], v[188:189], v[66:67]
	v_exp_f32_e32 v196, v74
	v_exp_f32_e32 v197, v75
	v_sub_f32_e32 v76, v76, v216
	v_sub_f32_e32 v77, v77, v216
	v_pk_add_f32 v[66:67], v[66:67], v[206:207]
	v_exp_f32_e32 v204, v92
	v_exp_f32_e32 v205, v93
	v_sub_f32_e32 v94, v94, v216
	v_sub_f32_e32 v95, v95, v216
	v_pk_add_f32 v[66:67], v[192:193], v[66:67]
	v_exp_f32_e32 v202, v76
	v_exp_f32_e32 v203, v77
	v_sub_f32_e32 v78, v78, v216
	v_sub_f32_e32 v79, v79, v216
	v_pk_add_f32 v[66:67], v[66:67], v[198:199]
	v_exp_f32_e32 v210, v94
	v_exp_f32_e32 v211, v95
	v_sub_f32_e32 v96, v96, v216
	v_sub_f32_e32 v97, v97, v216
	v_pk_add_f32 v[66:67], v[196:197], v[66:67]
	v_exp_f32_e32 v208, v78
	v_exp_f32_e32 v209, v79
	v_sub_f32_e32 v80, v80, v216
	v_sub_f32_e32 v81, v81, v216
	v_pk_add_f32 v[66:67], v[66:67], v[204:205]
	v_exp_f32_e32 v214, v96
	v_exp_f32_e32 v215, v97
	v_pk_add_f32 v[66:67], v[202:203], v[66:67]
	v_exp_f32_e32 v212, v80
	v_exp_f32_e32 v213, v81
	v_pk_add_f32 v[66:67], v[66:67], v[210:211]
	s_nop 0
	v_pk_add_f32 v[66:67], v[208:209], v[66:67]
	s_nop 0
	v_pk_add_f32 v[66:67], v[66:67], v[214:215]
	s_nop 0
	v_pk_add_f32 v[66:67], v[212:213], v[66:67]
	s_nop 0
	v_pk_mov_b32 v[68:69], v[174:175], v[66:67] op_sel:[1,0]
	v_mov_b32_e32 v217, v67
	v_pk_add_f32 v[216:217], v[68:69], v[216:217]
	s_nop 0
	v_mov_b32_e32 v183, v216
	s_branch .LBB0_239
.Ldl_ctxaddr:
	s_sub_i32 s20, s3, 63
	s_lshl_b64 s[4:5], s[20:21], 15
	v_lshl_add_u64 v[66:67], v[172:173], 0, s[4:5]
	s_branch .LBB0_232

.LBB0_230:
	s_cmp_lt_u32 s3, 63
	v_mov_b64_e32 v[66:67], v[178:179]
	s_cbranch_scc0 .Ldl_ctxaddr

.LBB0_233:
	s_and_b32 s4, s3, 1
	s_mul_i32 s5, s4, 0x4600
	v_add_u32_e32 v190, s5, v234
	ds_read_b128 v[66:69], v190
	ds_read_b128 v[70:73], v190 offset:32
	v_xor_b32_e32 v98, 0x80000000, v174
	v_mov_b32_e32 v99, v98
	v_mov_b32_e32 v100, v98
	v_mov_b32_e32 v101, v98
	v_mov_b32_e32 v102, v98
	v_mov_b32_e32 v103, v98
	v_mov_b32_e32 v104, v98
	v_mov_b32_e32 v105, v98
	v_mov_b32_e32 v106, v98
	v_mov_b32_e32 v107, v98
	v_mov_b32_e32 v108, v98
	v_mov_b32_e32 v109, v98
	v_mov_b32_e32 v110, v98
	v_mov_b32_e32 v111, v98
	v_mov_b32_e32 v112, v98
	v_mov_b32_e32 v113, v98
	ds_read_b128 v[76:79], v190 offset:4640
	ds_read_b128 v[182:185], v190 offset:64
	ds_read_b128 v[186:189], v190 offset:96
	s_waitcnt lgkmcnt(4)
	v_mfma_f32_32x32x16_bf16 v[114:129], v[66:69], v[130:133], v[98:113]
	v_xor_b32_e32 v66, 0x80000000, v175
	v_mov_b32_e32 v67, v66
	v_mov_b32_e32 v68, v66
	v_mov_b32_e32 v69, v66
	v_mov_b32_e32 v74, v66
	v_mov_b32_e32 v75, v66
	v_mov_b32_e32 v80, v66
	s_waitcnt lgkmcnt(3)
	v_mfma_f32_32x32x16_bf16 v[114:129], v[70:73], v[134:137], v[114:129]
	ds_read_b128 v[70:73], v190 offset:4608
	v_mov_b32_e32 v81, v66
	ds_read_b128 v[194:197], v190 offset:4672
	ds_read_b128 v[198:201], v190 offset:4704
	s_mov_b32 s6, 0x47800000
	s_nop 6
	v_exp_f32_e32 v192, v116
	s_waitcnt lgkmcnt(2)
	v_mfma_f32_32x32x16_bf16 v[98:113], v[70:73], v[130:133], v[98:113]
	v_mov_b32_e32 v70, v66
	v_mov_b32_e32 v71, v66
	v_mov_b32_e32 v72, v66
	v_mov_b32_e32 v73, v66
	v_exp_f32_e32 v193, v117
	v_exp_f32_e32 v202, v120
	v_exp_f32_e32 v203, v121
	v_mfma_f32_32x32x16_bf16 v[98:113], v[76:79], v[134:137], v[98:113]
	v_mov_b32_e32 v76, v66
	v_mov_b32_e32 v77, v66
	v_mov_b32_e32 v78, v66
	v_mov_b32_e32 v79, v66
	v_exp_f32_e32 v204, v122
	v_exp_f32_e32 v205, v123
	v_exp_f32_e32 v208, v124
	v_mfma_f32_32x32x16_bf16 v[82:97], v[182:185], v[138:141], v[66:81]
	s_nop 3
	v_exp_f32_e32 v184, v98
	v_exp_f32_e32 v185, v99
	v_exp_f32_e32 v190, v102
	v_exp_f32_e32 v191, v103
	v_exp_f32_e32 v209, v125
	v_exp_f32_e32 v212, v126
	v_exp_f32_e32 v213, v127
	v_mfma_f32_32x32x16_bf16 v[82:97], v[186:189], v[142:145], v[82:97]
	v_exp_f32_e32 v188, v114
	v_exp_f32_e32 v189, v115
	v_exp_f32_e32 v186, v100
	v_exp_f32_e32 v187, v101
	v_exp_f32_e32 v206, v110
	v_pk_add_f32 v[182:183], v[188:189], 0 op_sel_hi:[1,0]
	v_exp_f32_e32 v207, v111
	s_waitcnt lgkmcnt(1)
	v_mfma_f32_32x32x16_bf16 v[66:81], v[194:197], v[138:141], v[66:81]
	v_exp_f32_e32 v196, v118
	v_exp_f32_e32 v197, v119
	v_pk_add_f32 v[182:183], v[182:183], v[184:185]
	v_exp_f32_e32 v194, v104
	v_pk_add_f32 v[182:183], v[192:193], v[182:183]
	v_exp_f32_e32 v195, v105
	v_pk_add_f32 v[182:183], v[186:187], v[182:183]
	s_waitcnt lgkmcnt(0)
	v_mfma_f32_32x32x16_bf16 v[66:81], v[198:201], v[142:145], v[66:81]
	v_add_f32_e64 v182, v196, v182
	v_add_f32_e64 v183, v197, v183
	v_exp_f32_e32 v198, v106
	v_exp_f32_e32 v199, v107
	v_pk_add_f32 v[182:183], v[190:191], v[182:183]
	v_exp_f32_e32 v200, v108
	v_pk_add_f32 v[182:183], v[202:203], v[182:183]
	v_exp_f32_e32 v201, v109
	v_pk_add_f32 v[182:183], v[194:195], v[182:183]
	v_exp_f32_e32 v214, v128
	v_pk_add_f32 v[182:183], v[204:205], v[182:183]
	v_exp_f32_e32 v215, v129
	v_pk_add_f32 v[182:183], v[198:199], v[182:183]
	v_exp_f32_e32 v210, v112
	v_pk_add_f32 v[182:183], v[208:209], v[182:183]
	v_exp_f32_e32 v211, v113
	v_pk_add_f32 v[182:183], v[200:201], v[182:183]
	s_nop 0
	v_pk_add_f32 v[182:183], v[212:213], v[182:183]
	s_nop 0
	v_pk_add_f32 v[182:183], v[206:207], v[182:183]
	s_nop 0
	v_pk_add_f32 v[182:183], v[214:215], v[182:183]
	s_nop 0
	v_pk_add_f32 v[182:183], v[210:211], v[182:183]
	s_nop 0
	v_add_f32_e32 v237, v182, v183
	v_cmp_nge_f32_e32 vcc, s6, v237
	s_cbranch_vccnz .Ldl_slow1
	v_mov_b32_e32 v182, v174
.LBB0_236:
	v_add_u32_e32 v106, s5, v235
	v_add_u32_e32 v118, 0x2000, v106
	v_add_u32_e32 v126, 0x3000, v106
	ds_read2_b64 v[98:101], v118 offset0:128 offset1:130
	ds_read2_b64 v[106:109], v126 offset0:160 offset1:162
	v_cvt_pk_bf16_f32 v114, v188, v189
	v_cvt_pk_bf16_f32 v115, v192, v193
	v_cvt_pk_bf16_f32 v116, v196, v197
	v_cvt_pk_bf16_f32 v117, v202, v203
	ds_read2_b64 v[102:105], v118 offset0:132 offset1:134
	ds_read2_b64 v[110:113], v126 offset0:164 offset1:166
	s_waitcnt lgkmcnt(3)
	v_mfma_f32_32x32x16_bf16 v[2:17], v[98:101], v[114:117], v[2:17]
	v_cvt_pk_bf16_f32 v202, v204, v205
	v_cvt_pk_bf16_f32 v203, v208, v209
	v_cvt_pk_bf16_f32 v204, v212, v213
	v_cvt_pk_bf16_f32 v205, v214, v215
	v_cvt_pk_bf16_f32 v214, v190, v191
	v_exp_f32_e32 v190, v82
	v_exp_f32_e32 v191, v83
	s_waitcnt lgkmcnt(2)
	v_mfma_f32_32x32x16_bf16 v[18:33], v[106:109], v[114:117], v[18:33]
	v_cvt_pk_bf16_f32 v212, v184, v185
	v_exp_f32_e32 v184, v66
	v_exp_f32_e32 v185, v67
	v_cvt_pk_bf16_f32 v215, v194, v195
	ds_read2_b64 v[114:117], v118 offset0:136 offset1:138
	ds_read2_b64 v[118:121], v118 offset0:140 offset1:142
	ds_read2_b64 v[122:125], v126 offset0:168 offset1:170
	ds_read2_b64 v[126:129], v126 offset0:172 offset1:174
	v_exp_f32_e32 v194, v84
	v_exp_f32_e32 v195, v85
	s_waitcnt lgkmcnt(5)
	v_mfma_f32_32x32x16_bf16 v[2:17], v[102:105], v[202:205], v[2:17]
	v_cvt_pk_bf16_f32 v213, v186, v187
	v_exp_f32_e32 v186, v68
	v_exp_f32_e32 v187, v69
	v_cvt_pk_bf16_f32 v239, v200, v201
	v_exp_f32_e32 v200, v86
	v_exp_f32_e32 v201, v87
	v_pk_add_f32 v[216:217], v[190:191], 0 op_sel_hi:[1,0]
	s_waitcnt lgkmcnt(4)
	v_mfma_f32_32x32x16_bf16 v[18:33], v[110:113], v[202:205], v[18:33]
	v_exp_f32_e32 v188, v70
	v_exp_f32_e32 v189, v71
	v_pk_add_f32 v[216:217], v[216:217], v[184:185]
	v_cvt_pk_bf16_f32 v240, v206, v207
	v_exp_f32_e32 v206, v88
	v_exp_f32_e32 v207, v89
	v_pk_add_f32 v[216:217], v[194:195], v[216:217]
	s_waitcnt lgkmcnt(3)
	v_mfma_f32_32x32x16_bf16 v[2:17], v[114:117], v[212:215], v[2:17]
	v_exp_f32_e32 v192, v72
	v_exp_f32_e32 v193, v73
	v_pk_add_f32 v[216:217], v[186:187], v[216:217]
	v_cvt_pk_bf16_f32 v238, v198, v199
	v_exp_f32_e32 v198, v90
	v_exp_f32_e32 v199, v91
	v_pk_add_f32 v[216:217], v[200:201], v[216:217]
	s_waitcnt lgkmcnt(1)
	v_mfma_f32_32x32x16_bf16 v[18:33], v[122:125], v[212:215], v[18:33]
	v_exp_f32_e32 v196, v74
	v_exp_f32_e32 v197, v75
	v_pk_add_f32 v[216:217], v[188:189], v[216:217]
	v_exp_f32_e32 v204, v92
	v_exp_f32_e32 v205, v93
	v_pk_add_f32 v[216:217], v[206:207], v[216:217]
	v_exp_f32_e32 v202, v76
	v_exp_f32_e32 v203, v77
	v_pk_add_f32 v[216:217], v[192:193], v[216:217]
	v_cvt_pk_bf16_f32 v241, v210, v211
	v_exp_f32_e32 v210, v94
	v_exp_f32_e32 v211, v95
	v_pk_add_f32 v[216:217], v[198:199], v[216:217]
	v_exp_f32_e32 v208, v78
	v_exp_f32_e32 v209, v79
	v_pk_add_f32 v[216:217], v[196:197], v[216:217]
	v_mfma_f32_32x32x16_bf16 v[2:17], v[118:121], v[238:241], v[2:17]
	v_exp_f32_e32 v214, v96
	v_exp_f32_e32 v215, v97
	v_pk_add_f32 v[216:217], v[204:205], v[216:217]
	v_exp_f32_e32 v212, v80
	v_exp_f32_e32 v213, v81
	v_pk_add_f32 v[216:217], v[202:203], v[216:217]
	s_mov_b32 s5, 0x47800000
	s_waitcnt lgkmcnt(0)
	v_mfma_f32_32x32x16_bf16 v[18:33], v[126:129], v[238:241], v[18:33]
	v_add_f32_e64 v216, v210, v216
	v_add_f32_e64 v217, v211, v217
	v_add_f32_e64 v216, v208, v216
	v_add_f32_e64 v217, v209, v217
	v_add_f32_e64 v216, v214, v216
	v_add_f32_e64 v217, v215, v217
	v_pk_add_f32 v[216:217], v[212:213], v[216:217]
	s_nop 0
	v_add_f32_e32 v217, v216, v217
	v_cmp_nge_f32_e32 vcc, s5, v217
	s_cbranch_vccnz .Ldl_slow2
	v_mov_b32_e32 v183, v175
